# scan producer V-chunk staging remapped so 4 lanes fetch one row's contiguous 64B (16 instead of 64 cache lines per load instruction); same LDS image
# speedup vs baseline: 1.2341x; 1.2341x over previous
.LBB0_280:
	s_or_b64 exec, exec, s[0:1]
	v_readlane_b32 s8, v251, 39
	v_readlane_b32 s9, v251, 40
	s_ashr_i32 s14, s15, 6
	v_and_b32_e32 v174, 63, v161
	v_cndmask_b32_e64 v1, 0, 1, s[8:9]
	v_and_b32_e32 v0, 15, v161
	v_bfe_u32 v47, v161, 4, 2
	s_mov_b64 s[0:1], -1
	s_cmp_lt_i32 s14, 4
	v_cmp_ne_u32_e64 s[38:39], 1, v1
	s_cbranch_scc1 .LBB0_312
	s_and_b64 vcc, exec, s[38:39]
	s_cbranch_vccnz .LBB0_311
	v_add_u32_e32 v53, 0xffffff00, v161
	v_ashrrev_i32_e32 v175, 3, v53
	s_movk_i32 s0, 0x410
	v_lshl_or_b32 v1, s14, 4, v0
	s_waitcnt lgkmcnt(0)
	v_mul_lo_u32 v3, v175, s0
	v_readlane_b32 s0, v254, 38
	s_waitcnt vmcnt(0)
	v_subrev_u32_e32 v6, 64, v1
	v_and_b32_e32 v1, 7, v161
	v_add_u32_e32 v7, s0, v3
	v_readlane_b32 s0, v253, 53
	v_lshlrev_b32_e32 v4, 3, v1
	v_mov_b32_e32 v5, v2
	v_readlane_b32 s1, v253, 54
	v_lshlrev_b32_e32 v176, 3, v47
	v_lshlrev_b32_e32 v9, 1, v161
	v_lshl_add_u64 v[36:37], s[0:1], 0, v[4:5]
	v_readlane_b32 s0, v251, 22
	v_readlane_b32 s1, v251, 23
	v_lshlrev_b32_e32 v8, 4, v1
	v_lshl_add_u32 v177, v53, 6, 0
	v_lshl_add_u64 v[38:39], s[0:1], 0, v[4:5]
	s_movk_i32 s0, 0xa0
	v_mul_lo_u32 v5, v6, s0
	s_movk_i32 s0, 0xff68
	v_add_u32_e32 v185, 0, v5
	v_mul_lo_u32 v186, v6, s0
	v_lshlrev_b32_e32 v4, 2, v6
	v_add_u32_e32 v187, v185, v186
	v_sub_u32_e32 v46, v187, v4
	s_movk_i32 s0, 0x9c
	v_or_b32_e32 v40, 2, v176
	v_or_b32_e32 v3, 3, v176
	v_or_b32_e32 v43, 4, v176
	v_or_b32_e32 v42, 5, v176
	v_or_b32_e32 v45, 6, v176
	v_or_b32_e32 v44, 7, v176
	s_mov_b32 s98, 0x110000
	s_mov_b32 s99, 0
	v_lshlrev_b32_e32 v182, 4, v53
	v_and_b32_e32 v182, 0xffffffc0, v182
	v_bfe_u32 v183, v53, 4, 2
	v_and_b32_e32 v180, 3, v53
	v_lshlrev_b32_e32 v180, 1, v180
	v_xor_b32_e32 v180, v180, v183
	v_lshlrev_b32_e32 v180, 3, v180
	v_add_u32_e32 v180, v180, v182
	v_add_u32_e32 v180, 0xd800, v180
	v_xor_b32_e32 v181, 8, v180
	v_add_u32_e32 v9, 0, v4
	v_mul_u32_u24_e32 v184, 0x840, v47
	v_mad_u64_u32 v[48:49], s[0:1], v6, s0, v[46:47]
	v_lshlrev_b32_e32 v55, 1, v6
	v_add_u32_e32 v178, 0xd800, v177
	v_cmp_gt_u32_e64 s[40:41], 16, v174
	v_cmp_lt_u32_e64 s[42:43], 31, v174
	v_and_b32_e32 v179, 48, v161
	v_or_b32_e32 v1, 1, v176
	v_pk_mov_b32 v[50:51], v[44:45], v[42:43] op_sel:[1,0]
	v_mov_b32_e32 v52, v43
	v_mov_b32_e32 v54, v3
	v_mov_b32_e32 v41, v40
	v_add_u32_e32 v49, v9, v184
	v_add_u32_e32 v188, v7, v8
	s_mov_b32 s16, s2
	s_branch .LBB0_284

.LBB0_288:
	s_add_i32 s0, s17, 31
	s_lshr_b32 s18, s0, 5
	s_add_i32 s0, s18, 3
	s_and_b32 s19, s0, 0x46
	s_cmp_eq_u32 s19, 0
	s_cbranch_scc1 .LBB0_283
	s_and_b32 s0, s16, 15
	s_add_i32 s20, s18, -1
	s_ashr_i32 s9, s8, 31
	s_cmp_eq_u32 s20, 0
	v_add_u32_e32 v56, s8, v176
	s_cselect_b32 s1, 0, 32
	s_waitcnt vmcnt(0)
	v_add_u32_e32 v20, s1, v56
	v_ashrrev_i32_e32 v21, 31, v20
	v_lshl_add_u32 v58, s0, 7, v55
	v_mov_b32_e32 v59, v2
	v_lshlrev_b64 v[20:21], 11, v[20:21]
	v_lshl_add_u64 v[20:21], v[20:21], 0, v[58:59]
	v_lshlrev_b64 v[22:23], 1, v[20:21]
	v_lshl_add_u64 v[24:25], s[72:73], 0, v[22:23]
	v_add_co_u32_e32 v26, vcc, s33, v24
	v_lshl_add_u64 v[22:23], s[64:65], 0, v[22:23]
	s_nop 0
	v_addc_co_u32_e32 v27, vcc, 0, v25, vcc
	v_add_co_u32_e32 v28, vcc, s33, v22
	v_lshl_add_u64 v[20:21], v[20:21], 2, s[74:75]
	s_nop 0
	v_addc_co_u32_e32 v29, vcc, 0, v23, vcc
	s_mov_b32 s3, 0xe000
	v_add_co_u32_e32 v30, vcc, s3, v20
	v_readlane_b32 s10, v251, 37
	s_nop 0
	v_addc_co_u32_e32 v31, vcc, 0, v21, vcc
	v_readlane_b32 s11, v251, 38
	v_add_co_u32_e32 v32, vcc, s63, v24
	v_lshrrev_b32_e32 v6, 2, v53
	v_lshl_add_u32 v6, s0, 8, v6
	v_mov_b64_e32 v[4:5], s[10:11]
	v_addc_co_u32_e32 v33, vcc, 0, v25, vcc
	v_mad_i64_i32 v[4:5], s[10:11], v6, s93, v[4:5]
	v_add_co_u32_e32 v34, vcc, s63, v22
	v_readlane_b32 s10, v253, 63
	s_nop 0
	v_addc_co_u32_e32 v35, vcc, 0, v23, vcc
	v_lshl_add_u64 v[60:61], s[8:9], 1, v[4:5]
	v_and_b32_e32 v16, 3, v53
	v_lshlrev_b32_e32 v16, 4, v16
	v_mov_b32_e32 v17, 0
	v_lshl_add_u64 v[60:61], v[60:61], 0, v[16:17]
	v_readlane_b32 s11, v254, 0
	s_lshl_b32 s10, s1, 1
	v_add_co_u32_e32 v62, vcc, s67, v20
	v_lshl_add_u64 v[16:17], v[60:61], 0, s[10:11]
	s_nop 0
	v_addc_co_u32_e32 v63, vcc, 0, v21, vcc
	s_movk_i32 s10, 0x5000
	v_lshl_add_u64 v[8:9], v[16:17], 0, s[98:99]
	v_lshl_add_u64 v[12:13], v[8:9], 0, s[98:99]
	v_lshl_add_u64 v[4:5], v[12:13], 0, s[98:99]
	global_load_dwordx4 v[4:7], v[4:5], off
	global_load_dwordx4 v[12:15], v[12:13], off
	global_load_dwordx4 v[8:11], v[8:9], off
	s_nop 0
	global_load_dwordx4 v[16:19], v[16:17], off
	s_nop 0
	global_load_dwordx2 v[64:65], v[30:31], off
	global_load_dword v196, v[32:33], off
	global_load_dword v189, v[34:35], off
	global_load_dwordx2 v[66:67], v[62:63], off
	v_add_co_u32_e32 v30, vcc, s10, v24
	s_mov_b32 s9, 0xa000
	s_nop 0
	v_addc_co_u32_e32 v31, vcc, 0, v25, vcc
	v_add_co_u32_e32 v32, vcc, s10, v22
	s_mov_b32 s1, 0x8000
	s_nop 0
	v_addc_co_u32_e32 v33, vcc, 0, v23, vcc
	v_add_co_u32_e32 v34, vcc, s9, v20
	s_movk_i32 s12, 0x3000
	s_nop 0
	v_addc_co_u32_e32 v35, vcc, 0, v21, vcc
	v_add_co_u32_e32 v68, vcc, s66, v24
	s_movk_i32 s13, 0x1000
	s_nop 0
	v_addc_co_u32_e32 v69, vcc, 0, v25, vcc
	v_add_co_u32_e32 v70, vcc, s66, v22
	v_ashrrev_i32_e32 v57, 31, v56
	s_nop 0
	v_addc_co_u32_e32 v71, vcc, 0, v23, vcc
	global_load_dword v198, v[30:31], off
	global_load_dword v192, v[32:33], off
	global_load_dwordx2 v[62:63], v[34:35], off
	global_load_dword v197, v[68:69], off
	global_load_dword v190, v[70:71], off
	v_add_co_u32_e32 v30, vcc, s1, v20
	v_lshlrev_b64 v[78:79], 11, v[56:57]
	s_nop 0
	v_addc_co_u32_e32 v31, vcc, 0, v21, vcc
	v_add_co_u32_e32 v32, vcc, s12, v24
	v_lshl_add_u64 v[78:79], v[78:79], 0, v[58:59]
	s_nop 0
	v_addc_co_u32_e32 v33, vcc, 0, v25, vcc
	v_add_co_u32_e32 v34, vcc, s12, v22
	v_lshlrev_b64 v[80:81], 1, v[78:79]
	s_nop 0
	v_addc_co_u32_e32 v35, vcc, 0, v23, vcc
	v_add_co_u32_e32 v68, vcc, s63, v20
	v_lshl_add_u64 v[82:83], s[72:73], 0, v[80:81]
	s_nop 0
	v_addc_co_u32_e32 v69, vcc, 0, v21, vcc
	global_load_dwordx2 v[70:71], v[30:31], off
	global_load_dword v200, v[32:33], off
	global_load_dword v191, v[34:35], off
	global_load_dwordx2 v[72:73], v[68:69], off
	v_add_co_u32_e32 v30, vcc, s69, v24
	v_lshl_add_u64 v[80:81], s[64:65], 0, v[80:81]
	s_nop 0
	v_addc_co_u32_e32 v31, vcc, 0, v25, vcc
	v_add_co_u32_e32 v32, vcc, s69, v22
	v_lshl_add_u64 v[78:79], v[78:79], 2, s[74:75]
	s_nop 0
	v_addc_co_u32_e32 v33, vcc, 0, v23, vcc
	v_add_co_u32_e32 v34, vcc, s66, v20
	v_xor_b32_e32 v57, 1, v208
	s_nop 0
	v_addc_co_u32_e32 v35, vcc, 0, v21, vcc
	v_add_co_u32_e32 v68, vcc, s13, v24
	s_mov_b32 s28, 0xe000
	s_nop 0
	v_addc_co_u32_e32 v69, vcc, 0, v25, vcc
	v_add_co_u32_e32 v74, vcc, s13, v22
	s_mov_b32 s47, 0x8000
	s_nop 0
	v_addc_co_u32_e32 v75, vcc, 0, v23, vcc
	global_load_dword v202, v[30:31], off
	global_load_dword v195, v[32:33], off
	global_load_dwordx2 v[76:77], v[34:35], off
	global_load_dword v215, v[68:69], off
	global_load_dword v194, v[74:75], off
	v_add_co_u32_e32 v74, vcc, s69, v20
	s_mov_b32 s24, 0
	s_nop 0
	v_addc_co_u32_e32 v75, vcc, 0, v21, vcc
	v_add_co_u32_e32 v84, vcc, s33, v82
	global_load_dword v225, v[26:27], off
	global_load_dword v199, v[28:29], off
	global_load_dwordx2 v[68:69], v[20:21], off
	global_load_dword v193, v[22:23], off
	global_load_dword v201, v[24:25], off
	s_nop 0
	v_lshl_add_u64 v[24:25], v[60:61], 0, s[98:99]
	v_lshl_add_u64 v[28:29], v[24:25], 0, s[98:99]
	v_lshl_add_u64 v[20:21], v[28:29], 0, s[98:99]
	global_load_dwordx4 v[20:23], v[20:21], off
	global_load_dwordx4 v[28:31], v[28:29], off
	global_load_dwordx4 v[24:27], v[24:25], off
	global_load_dwordx4 v[32:35], v[60:61], off
	v_addc_co_u32_e32 v85, vcc, 0, v83, vcc
	v_add_co_u32_e32 v86, vcc, s33, v80
	v_add_u32_e32 v217, s8, v175
	s_nop 0
	v_addc_co_u32_e32 v87, vcc, 0, v81, vcc
	v_add_co_u32_e32 v88, vcc, s3, v78
	s_mov_b32 s3, 0xa000
	s_nop 0
	v_addc_co_u32_e32 v89, vcc, 0, v79, vcc
	v_add_co_u32_e32 v92, vcc, s63, v82
	s_add_i32 s21, s8, 32
	s_nop 0
	v_addc_co_u32_e32 v93, vcc, 0, v83, vcc
	v_add_co_u32_e32 v94, vcc, s63, v80
	s_sub_i32 s22, s17, 32
	s_nop 0
	v_addc_co_u32_e32 v95, vcc, 0, v81, vcc
	v_add_co_u32_e32 v90, vcc, s67, v78
	v_mov_b32_e32 v112, 0
	s_nop 0
	v_addc_co_u32_e32 v91, vcc, 0, v79, vcc
	v_add_co_u32_e32 v96, vcc, s10, v82
	v_mov_b32_e32 v113, 0
	s_nop 0
	v_addc_co_u32_e32 v97, vcc, 0, v83, vcc
	v_add_co_u32_e32 v98, vcc, s10, v80
	s_lshl_b32 s10, s0, 9
	s_nop 0
	v_addc_co_u32_e32 v99, vcc, 0, v81, vcc
	v_add_co_u32_e32 v100, vcc, s9, v78
	s_mov_b32 s9, 1
	s_nop 0
	v_addc_co_u32_e32 v101, vcc, 0, v79, vcc
	global_load_dwordx2 v[108:109], v[90:91], off
	global_load_dword v229, v[96:97], off
	global_load_dword v221, v[98:99], off
	s_nop 0
	global_load_dwordx2 v[90:91], v[100:101], off
	v_add_co_u32_e32 v96, vcc, s66, v82
	v_mov_b32_e32 v120, 0
	s_nop 0
	v_addc_co_u32_e32 v97, vcc, 0, v83, vcc
	v_add_co_u32_e32 v98, vcc, s66, v80
	v_mov_b32_e32 v121, 0
	s_nop 0
	v_addc_co_u32_e32 v99, vcc, 0, v81, vcc
	v_add_co_u32_e32 v100, vcc, s1, v78
	s_mov_b32 s1, s11
	s_nop 0
	v_addc_co_u32_e32 v101, vcc, 0, v79, vcc
	v_add_co_u32_e32 v102, vcc, s12, v82
	v_writelane_b32 v253, s0, 63
	s_nop 0
	v_addc_co_u32_e32 v103, vcc, 0, v83, vcc
	v_add_co_u32_e32 v104, vcc, s12, v80
	v_writelane_b32 v254, s1, 0
	s_nop 0
	v_addc_co_u32_e32 v105, vcc, 0, v81, vcc
	global_load_dword v231, v[96:97], off
	global_load_dword v223, v[98:99], off
	s_nop 0
	global_load_dwordx2 v[100:101], v[100:101], off
	s_nop 0
	global_load_dword v232, v[102:103], off
	global_load_dword v222, v[104:105], off
	v_add_co_u32_e32 v96, vcc, s63, v78
	v_mov_b32_e32 v124, 0
	s_nop 0
	v_addc_co_u32_e32 v97, vcc, 0, v79, vcc
	v_add_co_u32_e32 v98, vcc, s69, v82
	v_mov_b32_e32 v125, 0
	s_nop 0
	v_addc_co_u32_e32 v99, vcc, 0, v83, vcc
	v_add_co_u32_e32 v102, vcc, s69, v80
	v_mov_b32_e32 v110, 0
	s_nop 0
	v_addc_co_u32_e32 v103, vcc, 0, v81, vcc
	v_add_co_u32_e32 v104, vcc, s66, v78
	v_mov_b32_e32 v111, 0
	s_nop 0
	v_addc_co_u32_e32 v105, vcc, 0, v79, vcc
	global_load_dwordx2 v[114:115], v[96:97], off
	global_load_dword v234, v[98:99], off
	global_load_dword v226, v[102:103], off
	global_load_dwordx2 v[118:119], v[104:105], off
	v_add_co_u32_e32 v96, vcc, s13, v82
	v_mov_b32_e32 v116, 0
	s_nop 0
	v_addc_co_u32_e32 v97, vcc, 0, v83, vcc
	v_add_co_u32_e32 v98, vcc, s13, v80
	v_mov_b32_e32 v117, 0
	s_nop 0
	v_addc_co_u32_e32 v99, vcc, 0, v81, vcc
	v_add_co_u32_e32 v102, vcc, s69, v78
	v_mov_b32_e32 v122, 0
	s_nop 0
	v_addc_co_u32_e32 v103, vcc, 0, v79, vcc
	global_load_dword v235, v[96:97], off
	global_load_dword v227, v[98:99], off
	s_nop 0
	global_load_dwordx2 v[102:103], v[102:103], off
	s_nop 0
	global_load_dwordx2 v[104:105], v[74:75], off
	global_load_dword v237, v[84:85], off
	global_load_dword v230, v[86:87], off
	global_load_dword v224, v[80:81], off
	global_load_dword v233, v[82:83], off
	global_load_dwordx2 v[128:129], v[88:89], off
	global_load_dword v236, v[92:93], off
	global_load_dword v228, v[94:95], off
	global_load_dwordx2 v[106:107], v[78:79], off
	v_and_b32_e32 v80, 64, v208
	v_add_u32_e32 v74, 64, v80
	v_cmp_lt_i32_e32 vcc, v57, v74
	v_xor_b32_e32 v75, 2, v208
	v_add_u32_e32 v81, -16, v208
	v_cndmask_b32_e32 v57, v208, v57, vcc
	v_cmp_lt_i32_e32 vcc, v75, v74
	v_lshlrev_b32_e32 v57, 2, v57
	v_lshl_add_u64 v[78:79], v[38:39], 0, s[10:11]
	v_cndmask_b32_e32 v75, v208, v75, vcc
	v_lshlrev_b32_e32 v203, 2, v75
	v_xor_b32_e32 v75, 4, v208
	v_cmp_lt_i32_e32 vcc, v75, v74
	v_mov_b32_e32 v84, 0
	v_mov_b32_e32 v85, 0
	v_cndmask_b32_e32 v74, v208, v75, vcc
	v_cmp_lt_i32_e32 vcc, v81, v80
	v_lshlrev_b32_e32 v216, 2, v74
	v_lshl_add_u64 v[74:75], v[36:37], 0, s[10:11]
	v_cndmask_b32_e32 v81, v81, v208, vcc
	v_lshlrev_b32_e32 v218, 2, v81
	v_subrev_u32_e32 v81, 32, v208
	v_cmp_lt_i32_e32 vcc, v81, v80
	v_or_b32_e32 v80, v80, v0
	v_lshl_or_b32 v220, v80, 2, v209
	v_cndmask_b32_e32 v81, v81, v208, vcc
	v_lshlrev_b32_e32 v219, 2, v81
	v_mov_b32_e32 v80, 0
	v_mov_b32_e32 v81, 0
	v_mov_b32_e32 v88, 0
	v_mov_b32_e32 v89, 0
	v_mov_b32_e32 v94, 0
	v_mov_b32_e32 v95, 0
	v_mov_b32_e32 v98, 0
	v_mov_b32_e32 v99, 0
	v_mov_b32_e32 v82, 0
	v_mov_b32_e32 v83, 0
	v_mov_b32_e32 v86, 0
	v_mov_b32_e32 v87, 0
	v_mov_b32_e32 v92, 0
	v_mov_b32_e32 v93, 0
	v_mov_b32_e32 v96, 0
	v_mov_b32_e32 v97, 0
	v_mov_b32_e32 v123, 0
	v_mov_b32_e32 v126, 0
	v_mov_b32_e32 v127, 0
	s_mov_b32 s23, s17
	s_branch .LBB0_291

.LBB0_299:
	ds_write_b64 v180, v[32:33]
	ds_write_b64 v181, v[34:35]
	s_add_i32 s25, s24, 2
	ds_write_b64 v180, v[24:25] offset:4096
	ds_write_b64 v181, v[26:27] offset:4096
	s_min_i32 s0, s25, s20
	ds_write_b64 v180, v[28:29] offset:8192
	ds_write_b64 v181, v[30:31] offset:8192
	ds_write_b64 v180, v[20:21] offset:12288
	s_lshl_b32 s0, s0, 5
	ds_write_b64 v181, v[22:23] offset:12288
	v_add_u32_e32 v20, s0, v56
	v_ashrrev_i32_e32 v21, 31, v20
	v_lshlrev_b64 v[20:21], 11, v[20:21]
	v_lshl_add_u64 v[20:21], v[20:21], 0, v[58:59]
	v_lshl_add_u64 v[22:23], v[20:21], 2, s[74:75]
	v_lshlrev_b64 v[20:21], 1, v[20:21]
	v_add_co_u32_e32 v26, vcc, s69, v22
	v_lshl_add_u64 v[24:25], s[64:65], 0, v[20:21]
	s_nop 0
	v_addc_co_u32_e32 v27, vcc, 0, v23, vcc
	v_lshlrev_b32_e32 v244, 16, v224
	v_and_b32_e32 v245, 0xffff0000, v224
	v_lshl_add_u64 v[20:21], s[72:73], 0, v[20:21]
	global_load_dwordx2 v[106:107], v[22:23], off
	global_load_dword v224, v[24:25], off
	global_load_dword v233, v[20:21], off
	global_load_dwordx2 v[102:103], v[26:27], off
	v_add_co_u32_e32 v26, vcc, s69, v24
	v_lshlrev_b32_e32 v246, 16, v227
	s_nop 0
	v_addc_co_u32_e32 v27, vcc, 0, v25, vcc
	v_add_co_u32_e32 v28, vcc, s69, v20
	v_and_b32_e32 v247, 0xffff0000, v227
	s_nop 0
	v_addc_co_u32_e32 v29, vcc, 0, v21, vcc
	v_add_co_u32_e32 v30, vcc, s66, v22
	v_lshlrev_b32_e32 v248, 16, v226
	s_nop 0
	v_addc_co_u32_e32 v31, vcc, 0, v23, vcc
	v_add_co_u32_e32 v32, vcc, s66, v24
	v_and_b32_e32 v249, 0xffff0000, v226
	s_nop 0
	v_addc_co_u32_e32 v33, vcc, 0, v25, vcc
	v_add_co_u32_e32 v34, vcc, s66, v20
	v_lshlrev_b32_e32 v172, 16, v222
	s_nop 0
	v_addc_co_u32_e32 v35, vcc, 0, v21, vcc
	v_and_b32_e32 v173, 0xffff0000, v222
	v_lshlrev_b32_e32 v170, 16, v223
	v_and_b32_e32 v171, 0xffff0000, v223
	global_load_dword v227, v[26:27], off offset:-4096
	global_load_dword v235, v[28:29], off offset:-4096
	global_load_dword v234, v[28:29], off
	global_load_dword v222, v[32:33], off offset:-4096
	global_load_dword v232, v[34:35], off offset:-4096
	global_load_dword v231, v[34:35], off
	global_load_dword v223, v[32:33], off
	global_load_dword v226, v[26:27], off
	v_add_co_u32_e32 v26, vcc, s63, v22
	v_lshlrev_b32_e32 v168, 16, v221
	s_nop 0
	v_addc_co_u32_e32 v27, vcc, 0, v23, vcc
	v_add_co_u32_e32 v28, vcc, s47, v22
	v_and_b32_e32 v169, 0xffff0000, v221
	s_nop 0
	v_addc_co_u32_e32 v29, vcc, 0, v23, vcc
	v_add_co_u32_e32 v32, vcc, s3, v22
	v_lshlrev_b32_e32 v166, 16, v228
	s_nop 0
	v_addc_co_u32_e32 v33, vcc, 0, v23, vcc
	global_load_dwordx2 v[118:119], v[30:31], off
	global_load_dwordx2 v[114:115], v[26:27], off
	global_load_dwordx2 v[100:101], v[28:29], off
	global_load_dwordx2 v[90:91], v[32:33], off
	v_add_co_u32_e32 v26, vcc, s63, v24
	v_and_b32_e32 v167, 0xffff0000, v228
	s_nop 0
	v_addc_co_u32_e32 v27, vcc, 0, v25, vcc
	v_add_co_u32_e32 v28, vcc, s63, v20
	s_ashr_i32 s1, s0, 31
	s_nop 0
	v_addc_co_u32_e32 v29, vcc, 0, v21, vcc
	v_add_co_u32_e32 v30, vcc, s67, v22
	global_load_dword v221, v[26:27], off offset:-4096
	global_load_dword v229, v[28:29], off offset:-4096
	global_load_dword v236, v[28:29], off
	global_load_dword v228, v[26:27], off
	v_addc_co_u32_e32 v31, vcc, 0, v23, vcc
	v_add_co_u32_e32 v22, vcc, s28, v22
	ds_bpermute_b32 v26, v218, v134
	s_nop 0
	v_addc_co_u32_e32 v23, vcc, 0, v23, vcc
	ds_bpermute_b32 v27, v218, v137
	v_add_co_u32_e32 v24, vcc, s33, v24
	v_lshlrev_b32_e32 v158, 16, v230
	s_nop 0
	v_addc_co_u32_e32 v25, vcc, 0, v25, vcc
	v_add_co_u32_e32 v20, vcc, s33, v20
	v_and_b32_e32 v159, 0xffff0000, v230
	s_nop 0
	v_addc_co_u32_e32 v21, vcc, 0, v21, vcc
	global_load_dwordx2 v[108:109], v[30:31], off
	global_load_dwordx2 v[128:129], v[22:23], off
	global_load_dword v230, v[24:25], off
	global_load_dword v237, v[20:21], off
	v_lshl_add_u64 v[32:33], s[0:1], 1, v[60:61]
	s_waitcnt lgkmcnt(1)
	v_add_f32_e32 v20, v134, v26
	s_waitcnt lgkmcnt(0)
	v_add_f32_e32 v21, v137, v27
	v_cndmask_b32_e64 v162, v20, v134, s[40:41]
	v_cndmask_b32_e64 v163, v21, v137, s[40:41]
	v_lshl_add_u64 v[24:25], v[32:33], 0, s[98:99]
	v_lshl_add_u64 v[28:29], v[24:25], 0, s[98:99]
	v_lshl_add_u64 v[20:21], v[28:29], 0, s[98:99]
	global_load_dwordx4 v[20:23], v[20:21], off
	global_load_dwordx4 v[28:31], v[28:29], off
	global_load_dwordx4 v[24:27], v[24:25], off
	s_nop 0
	global_load_dwordx4 v[32:35], v[32:33], off
	ds_bpermute_b32 v242, v219, v162
	ds_bpermute_b32 v243, v219, v163
	s_waitcnt lgkmcnt(1)
	v_add_f32_e32 v242, v162, v242
	s_waitcnt lgkmcnt(0)
	v_add_f32_e32 v243, v163, v243
	v_cndmask_b32_e64 v162, v162, v242, s[42:43]
	v_cndmask_b32_e64 v243, v163, v243, s[42:43]
	v_sub_f32_e32 v250, v162, v134
	v_sub_f32_e32 v211, v243, v137
	v_add_f32_e32 v207, v136, v250
	v_add_f32_e32 v139, v139, v211
	ds_bpermute_b32 v242, v220, v162
	v_exp_f32_e32 v162, v207
	v_exp_f32_e32 v163, v139
	v_exp_f32_e64 v207, -v207
	v_exp_f32_e64 v139, -v139
	v_add_f32_e32 v147, v147, v211
	v_pk_mul_f32 v[162:163], v[162:163], v[244:245]
	v_mul_f32_e32 v131, v131, v207
	v_add_f32_e32 v207, v138, v250
	v_cvt_pk_bf16_f32 v162, v162, v163
	v_mul_f32_e32 v163, v241, v139
	v_exp_f32_e32 v138, v207
	v_exp_f32_e32 v139, v147
	v_cvt_pk_bf16_f32 v163, v131, v163
	v_exp_f32_e64 v131, -v207
	v_exp_f32_e64 v147, -v147
	v_pk_mul_f32 v[138:139], v[138:139], v[246:247]
	v_add_f32_e32 v146, v146, v250
	v_cvt_pk_bf16_f32 v138, v138, v139
	v_mul_f32_e32 v131, v239, v131
	v_mul_f32_e32 v139, v240, v147
	v_add_f32_e32 v147, v149, v211
	v_cvt_pk_bf16_f32 v207, v131, v139
	ds_write2_b32 v49, v162, v138 offset1:66
	v_exp_f32_e32 v138, v146
	v_exp_f32_e32 v139, v147
	v_exp_f32_e64 v146, -v146
	v_exp_f32_e64 v147, -v147
	v_add_u32_e32 v131, 0x2000, v49
	v_pk_mul_f32 v[138:139], v[138:139], v[248:249]
	v_add_f32_e32 v148, v148, v250
	v_add_f32_e32 v143, v143, v211
	ds_write2_b32 v131, v163, v207 offset0:64 offset1:130
	v_cvt_pk_bf16_f32 v131, v138, v139
	v_pk_mul_f32 v[138:139], v[156:157], v[146:147]
	v_exp_f32_e32 v146, v148
	v_exp_f32_e32 v147, v143
	v_exp_f32_e64 v148, -v148
	v_exp_f32_e64 v149, -v143
	v_cvt_pk_bf16_f32 v156, v138, v139
	v_pk_mul_f32 v[138:139], v[146:147], v[172:173]
	v_add_f32_e32 v142, v142, v250
	v_cvt_pk_bf16_f32 v143, v138, v139
	v_pk_mul_f32 v[138:139], v[154:155], v[148:149]
	ds_write2_b32 v49, v131, v143 offset0:132 offset1:198
	v_add_f32_e32 v143, v145, v211
	v_cvt_pk_bf16_f32 v146, v138, v139
	v_exp_f32_e32 v138, v142
	v_exp_f32_e32 v139, v143
	v_exp_f32_e64 v142, -v142
	v_exp_f32_e64 v143, -v143
	v_add_u32_e32 v131, 0x2200, v49
	v_pk_mul_f32 v[138:139], v[138:139], v[170:171]
	v_add_f32_e32 v144, v144, v250
	v_add_f32_e32 v141, v141, v211
	ds_write2_b32 v131, v156, v146 offset0:68 offset1:134
	v_cvt_pk_bf16_f32 v131, v138, v139
	v_pk_mul_f32 v[138:139], v[152:153], v[142:143]
	v_exp_f32_e32 v142, v144
	v_exp_f32_e32 v143, v141
	v_exp_f32_e64 v144, -v144
	v_exp_f32_e64 v145, -v141
	v_cvt_pk_bf16_f32 v147, v138, v139
	v_pk_mul_f32 v[138:139], v[142:143], v[168:169]
	v_add_u32_e32 v143, 0x400, v49
	v_cvt_pk_bf16_f32 v141, v138, v139
	v_pk_mul_f32 v[138:139], v[150:151], v[144:145]
	v_add_f32_e32 v140, v140, v250
	v_add_f32_e32 v135, v135, v211
	v_cvt_pk_bf16_f32 v142, v138, v139
	ds_write2_b32 v143, v131, v141 offset0:8 offset1:74
	v_exp_f32_e32 v138, v140
	v_exp_f32_e32 v139, v135
	v_exp_f32_e64 v140, -v140
	v_exp_f32_e64 v141, -v135
	v_add_u32_e32 v131, 0x2400, v49
	ds_write2_b32 v131, v147, v142 offset0:72 offset1:138
	v_mov_b32_e32 v131, v133
	v_pk_mul_f32 v[138:139], v[138:139], v[166:167]
	v_pk_mul_f32 v[130:131], v[130:131], v[140:141]
	v_add_f32_e32 v133, v134, v250
	v_add_f32_e32 v137, v137, v211
	v_cvt_pk_bf16_f32 v138, v138, v139
	v_exp_f32_e32 v134, v133
	v_exp_f32_e32 v135, v137
	v_cvt_pk_bf16_f32 v139, v130, v131
	v_exp_f32_e64 v130, -v133
	v_exp_f32_e64 v131, -v137
	ds_bpermute_b32 v136, v220, v243
	v_mov_b32_e32 v133, v238
	v_pk_mul_f32 v[134:135], v[134:135], v[158:159]
	v_pk_mul_f32 v[130:131], v[132:133], v[130:131]
	v_cvt_pk_bf16_f32 v134, v134, v135
	v_cvt_pk_bf16_f32 v135, v130, v131
	v_add_u32_e32 v130, 0x2600, v49
	ds_write2_b32 v143, v138, v134 offset0:140 offset1:206
	ds_write2_b32 v130, v139, v135 offset0:76 offset1:142
	v_perm_b32 v130, v207, v163, s71
	v_perm_b32 v131, v146, v156, s71
	v_perm_b32 v132, v142, v147, s71
	v_perm_b32 v133, v135, v139, s71
	v_add_u32_e32 v134, v185, v179
	ds_write_b128 v134, v[130:133] offset:16896
	v_perm_b32 v130, v207, v163, s62
	v_perm_b32 v131, v146, v156, s62
	v_perm_b32 v132, v142, v147, s62
	v_perm_b32 v133, v135, v139, s62
	ds_write_b128 v134, v[130:133] offset:16976
	s_and_saveexec_b64 s[0:1], s[40:41]
	s_cbranch_execz .LBB0_301
	s_waitcnt lgkmcnt(11)
	v_exp_f32_e32 v130, v242
	s_waitcnt lgkmcnt(4)
	v_exp_f32_e32 v131, v136
	ds_write_b64 v187, v[130:131] offset:27136

.LBB0_309:
	ds_write_b64 v180, v[16:17] offset:16384
	ds_write_b64 v181, v[18:19] offset:16384
	s_add_i32 s0, s24, 3
	ds_write_b64 v180, v[8:9] offset:20480
	ds_write_b64 v181, v[10:11] offset:20480
	s_min_i32 s0, s0, s20
	ds_write_b64 v180, v[12:13] offset:24576
	ds_write_b64 v181, v[14:15] offset:24576
	ds_write_b64 v180, v[4:5] offset:28672
	s_lshl_b32 s0, s0, 5
	ds_write_b64 v181, v[6:7] offset:28672
	v_add_u32_e32 v4, s0, v56
	v_ashrrev_i32_e32 v5, 31, v4
	v_lshlrev_b64 v[4:5], 11, v[4:5]
	v_lshl_add_u64 v[4:5], v[4:5], 0, v[58:59]
	v_lshl_add_u64 v[6:7], v[4:5], 2, s[74:75]
	v_lshlrev_b64 v[4:5], 1, v[4:5]
	v_add_co_u32_e32 v10, vcc, s69, v6
	v_lshl_add_u64 v[8:9], s[64:65], 0, v[4:5]
	s_nop 0
	v_addc_co_u32_e32 v11, vcc, 0, v7, vcc
	v_lshlrev_b32_e32 v162, 16, v193
	v_and_b32_e32 v163, 0xffff0000, v193
	v_lshl_add_u64 v[4:5], s[72:73], 0, v[4:5]
	global_load_dwordx2 v[68:69], v[6:7], off
	global_load_dword v193, v[8:9], off
	global_load_dword v201, v[4:5], off
	global_load_dwordx2 v[104:105], v[10:11], off
	v_add_co_u32_e32 v10, vcc, s69, v8
	v_lshlrev_b32_e32 v244, 16, v194
	s_nop 0
	v_addc_co_u32_e32 v11, vcc, 0, v9, vcc
	v_add_co_u32_e32 v12, vcc, s69, v4
	v_and_b32_e32 v245, 0xffff0000, v194
	s_nop 0
	v_addc_co_u32_e32 v13, vcc, 0, v5, vcc
	v_add_co_u32_e32 v14, vcc, s66, v6
	v_lshlrev_b32_e32 v246, 16, v195
	s_nop 0
	v_addc_co_u32_e32 v15, vcc, 0, v7, vcc
	v_add_co_u32_e32 v16, vcc, s66, v8
	v_and_b32_e32 v247, 0xffff0000, v195
	s_nop 0
	v_addc_co_u32_e32 v17, vcc, 0, v9, vcc
	v_add_co_u32_e32 v18, vcc, s66, v4
	v_lshlrev_b32_e32 v156, 16, v191
	s_nop 0
	v_addc_co_u32_e32 v19, vcc, 0, v5, vcc
	v_and_b32_e32 v157, 0xffff0000, v191
	v_lshlrev_b32_e32 v154, 16, v190
	v_and_b32_e32 v155, 0xffff0000, v190
	global_load_dword v194, v[10:11], off offset:-4096
	global_load_dword v215, v[12:13], off offset:-4096
	global_load_dword v202, v[12:13], off
	global_load_dword v191, v[16:17], off offset:-4096
	global_load_dword v200, v[18:19], off offset:-4096
	global_load_dword v197, v[18:19], off
	global_load_dword v190, v[16:17], off
	global_load_dword v195, v[10:11], off
	v_add_co_u32_e32 v10, vcc, s63, v6
	v_lshlrev_b32_e32 v152, 16, v192
	s_nop 0
	v_addc_co_u32_e32 v11, vcc, 0, v7, vcc
	v_add_co_u32_e32 v12, vcc, s47, v6
	v_and_b32_e32 v153, 0xffff0000, v192
	s_nop 0
	v_addc_co_u32_e32 v13, vcc, 0, v7, vcc
	v_add_co_u32_e32 v16, vcc, s3, v6
	v_lshlrev_b32_e32 v150, 16, v189
	s_nop 0
	v_addc_co_u32_e32 v17, vcc, 0, v7, vcc
	global_load_dwordx2 v[76:77], v[14:15], off
	global_load_dwordx2 v[72:73], v[10:11], off
	global_load_dwordx2 v[70:71], v[12:13], off
	global_load_dwordx2 v[62:63], v[16:17], off
	v_add_co_u32_e32 v10, vcc, s63, v8
	v_and_b32_e32 v151, 0xffff0000, v189
	s_nop 0
	v_addc_co_u32_e32 v11, vcc, 0, v9, vcc
	v_add_co_u32_e32 v12, vcc, s63, v4
	s_ashr_i32 s1, s0, 31
	s_nop 0
	v_addc_co_u32_e32 v13, vcc, 0, v5, vcc
	v_add_co_u32_e32 v14, vcc, s67, v6
	global_load_dword v192, v[10:11], off offset:-4096
	global_load_dword v198, v[12:13], off offset:-4096
	global_load_dword v196, v[12:13], off
	global_load_dword v189, v[10:11], off
	v_addc_co_u32_e32 v15, vcc, 0, v7, vcc
	v_add_co_u32_e32 v6, vcc, s28, v6
	ds_bpermute_b32 v10, v218, v145
	s_nop 0
	v_addc_co_u32_e32 v7, vcc, 0, v7, vcc
	ds_bpermute_b32 v11, v218, v167
	v_add_co_u32_e32 v8, vcc, s33, v8
	v_lshlrev_b32_e32 v148, 16, v199
	s_nop 0
	v_addc_co_u32_e32 v9, vcc, 0, v9, vcc
	v_add_co_u32_e32 v4, vcc, s33, v4
	v_and_b32_e32 v149, 0xffff0000, v199
	s_nop 0
	v_addc_co_u32_e32 v5, vcc, 0, v5, vcc
	global_load_dwordx2 v[66:67], v[14:15], off
	global_load_dwordx2 v[64:65], v[6:7], off
	global_load_dword v199, v[8:9], off
	global_load_dword v225, v[4:5], off
	v_lshl_add_u64 v[16:17], s[0:1], 1, v[60:61]
	s_waitcnt lgkmcnt(1)
	v_add_f32_e32 v4, v145, v10
	s_waitcnt lgkmcnt(0)
	v_add_f32_e32 v5, v167, v11
	v_cndmask_b32_e64 v207, v4, v145, s[40:41]
	v_cndmask_b32_e64 v211, v5, v167, s[40:41]
	v_lshl_add_u64 v[8:9], v[16:17], 0, s[98:99]
	v_lshl_add_u64 v[12:13], v[8:9], 0, s[98:99]
	v_lshl_add_u64 v[4:5], v[12:13], 0, s[98:99]
	global_load_dwordx4 v[4:7], v[4:5], off
	global_load_dwordx4 v[12:15], v[12:13], off
	global_load_dwordx4 v[8:11], v[8:9], off
	s_nop 0
	global_load_dwordx4 v[16:19], v[16:17], off
	ds_bpermute_b32 v242, v219, v207
	ds_bpermute_b32 v243, v219, v211
	s_waitcnt lgkmcnt(1)
	v_add_f32_e32 v242, v207, v242
	s_waitcnt lgkmcnt(0)
	v_add_f32_e32 v243, v211, v243
	v_cndmask_b32_e64 v207, v207, v242, s[42:43]
	v_cndmask_b32_e64 v211, v211, v243, s[42:43]
	ds_bpermute_b32 v242, v220, v207
	v_sub_f32_e32 v207, v207, v145
	v_sub_f32_e32 v243, v211, v167
	v_add_f32_e32 v144, v144, v207
	v_add_f32_e32 v250, v143, v243
	v_exp_f32_e32 v248, v144
	ds_bpermute_b32 v143, v220, v211
	v_exp_f32_e64 v144, -v144
	v_exp_f32_e64 v211, -v250
	v_exp_f32_e32 v249, v250
	v_mul_f32_e32 v141, v141, v144
	v_mul_f32_e32 v144, v169, v211
	v_pk_mul_f32 v[162:163], v[248:249], v[162:163]
	v_cvt_pk_bf16_f32 v144, v141, v144
	v_add_f32_e32 v141, v142, v207
	v_add_f32_e32 v142, v147, v243
	v_cvt_pk_bf16_f32 v250, v162, v163
	v_exp_f32_e32 v162, v141
	v_exp_f32_e32 v163, v142
	v_exp_f32_e64 v248, -v141
	v_exp_f32_e64 v249, -v142
	v_add_u32_e32 v169, v46, v184
	v_pk_mul_f32 v[162:163], v[162:163], v[244:245]
	v_mov_b32_e32 v141, v139
	v_cvt_pk_bf16_f32 v142, v162, v163
	v_add_u32_e32 v163, 0x6c00, v169
	v_pk_mul_f32 v[140:141], v[140:141], v[248:249]
	ds_write2_b32 v163, v250, v142 offset1:66
	v_add_f32_e32 v142, v146, v207
	v_add_f32_e32 v147, v241, v243
	v_cvt_pk_bf16_f32 v162, v140, v141
	v_exp_f32_e32 v140, v142
	v_exp_f32_e32 v141, v147
	v_exp_f32_e64 v146, -v142
	v_exp_f32_e64 v147, -v147
	v_add_u32_e32 v139, 0x8c00, v169
	ds_write2_b32 v139, v144, v162 offset0:64 offset1:130
	v_mov_b32_e32 v139, v166
	v_pk_mul_f32 v[140:141], v[140:141], v[246:247]
	v_pk_mul_f32 v[138:139], v[138:139], v[146:147]
	v_add_f32_e32 v146, v239, v207
	v_add_f32_e32 v147, v240, v243
	v_cvt_pk_bf16_f32 v142, v140, v141
	v_exp_f32_e32 v140, v146
	v_exp_f32_e32 v141, v147
	v_exp_f32_e64 v146, -v146
	v_exp_f32_e64 v147, -v147
	v_cvt_pk_bf16_f32 v166, v138, v139
	v_pk_mul_f32 v[138:139], v[140:141], v[156:157]
	v_mul_f32_e32 v135, v135, v146
	v_cvt_pk_bf16_f32 v138, v138, v139
	v_mul_f32_e32 v139, v159, v147
	v_add_f32_e32 v140, v173, v207
	v_add_f32_e32 v141, v238, v243
	v_cvt_pk_bf16_f32 v146, v135, v139
	ds_write2_b32 v163, v142, v138 offset0:132 offset1:198
	v_exp_f32_e32 v138, v140
	v_exp_f32_e32 v139, v141
	v_exp_f32_e64 v140, -v140
	v_exp_f32_e64 v141, -v141
	v_add_u32_e32 v135, 0x8e00, v169
	ds_write2_b32 v135, v166, v146 offset0:68 offset1:134
	v_mov_b32_e32 v135, v137
	v_pk_mul_f32 v[138:139], v[138:139], v[154:155]
	v_pk_mul_f32 v[134:135], v[134:135], v[140:141]
	v_add_f32_e32 v137, v171, v207
	v_add_f32_e32 v140, v172, v243
	v_cvt_pk_bf16_f32 v142, v138, v139
	v_exp_f32_e32 v138, v137
	v_exp_f32_e32 v139, v140
	v_cvt_pk_bf16_f32 v141, v134, v135
	v_exp_f32_e64 v134, -v137
	v_exp_f32_e64 v135, -v140
	v_mov_b32_e32 v137, v131
	v_pk_mul_f32 v[138:139], v[138:139], v[152:153]
	v_add_u32_e32 v131, 0x9000, v169
	v_pk_mul_f32 v[134:135], v[136:137], v[134:135]
	v_add_f32_e32 v136, v168, v207
	v_add_f32_e32 v137, v170, v243
	v_cvt_pk_bf16_f32 v138, v138, v139
	v_cvt_pk_bf16_f32 v139, v134, v135
	v_exp_f32_e32 v134, v136
	v_exp_f32_e32 v135, v137
	v_exp_f32_e64 v136, -v136
	v_exp_f32_e64 v137, -v137
	ds_write2_b32 v131, v141, v139 offset0:72 offset1:138
	v_mov_b32_e32 v131, v133
	v_add_u32_e32 v140, 0x7000, v169
	v_pk_mul_f32 v[134:135], v[134:135], v[150:151]
	v_pk_mul_f32 v[130:131], v[130:131], v[136:137]
	v_add_f32_e32 v133, v145, v207
	v_add_f32_e32 v136, v167, v243
	ds_write2_b32 v140, v142, v138 offset0:8 offset1:74
	v_cvt_pk_bf16_f32 v138, v134, v135
	v_exp_f32_e32 v134, v133
	v_exp_f32_e32 v135, v136
	v_cvt_pk_bf16_f32 v137, v130, v131
	v_exp_f32_e64 v130, -v133
	v_exp_f32_e64 v131, -v136
	v_mov_b32_e32 v133, v158
	v_pk_mul_f32 v[134:135], v[134:135], v[148:149]
	v_pk_mul_f32 v[130:131], v[132:133], v[130:131]
	v_cvt_pk_bf16_f32 v134, v134, v135
	v_cvt_pk_bf16_f32 v135, v130, v131
	v_add_u32_e32 v130, 0x9200, v169
	ds_write2_b32 v140, v138, v134 offset0:140 offset1:206
	ds_write2_b32 v130, v137, v135 offset0:76 offset1:142
	v_perm_b32 v130, v162, v144, s71
	v_perm_b32 v131, v146, v166, s71
	v_perm_b32 v132, v139, v141, s71
	v_perm_b32 v133, v135, v137, s71
	v_add_u32_e32 v134, v48, v179
	ds_write_b128 v134, v[130:133] offset:44544
	v_perm_b32 v130, v162, v144, s62
	v_perm_b32 v131, v146, v166, s62
	v_perm_b32 v132, v139, v141, s62
	v_perm_b32 v133, v135, v137, s62
	ds_write_b128 v134, v[130:133] offset:44624
	s_and_saveexec_b64 s[0:1], s[40:41]
	s_cbranch_execz .LBB0_290
	s_waitcnt lgkmcnt(11)
	v_exp_f32_e32 v130, v242
	s_waitcnt lgkmcnt(10)
	v_exp_f32_e32 v131, v143
	v_add_u32_e32 v132, v48, v186
	ds_write_b64 v132, v[130:131] offset:54784
	s_branch .LBB0_290

	.amdhsa_kernel _Z8yoco_fwd6Params
		.amdhsa_group_segment_fixed_size 0
		.amdhsa_private_segment_fixed_size 0
		.amdhsa_kernarg_size 416
		.amdhsa_user_sgpr_count 2
		.amdhsa_user_sgpr_dispatch_ptr 0
		.amdhsa_user_sgpr_queue_ptr 0
		.amdhsa_user_sgpr_kernarg_segment_ptr 1
		.amdhsa_user_sgpr_dispatch_id 0
		.amdhsa_user_sgpr_kernarg_preload_length 0
		.amdhsa_user_sgpr_kernarg_preload_offset 0
		.amdhsa_user_sgpr_private_segment_size 0
		.amdhsa_uses_dynamic_stack 0
		.amdhsa_enable_private_segment 0
		.amdhsa_system_sgpr_workgroup_id_x 1
		.amdhsa_system_sgpr_workgroup_id_y 0
		.amdhsa_system_sgpr_workgroup_id_z 0
		.amdhsa_system_sgpr_workgroup_info 0
		.amdhsa_system_vgpr_workitem_id 2
		.amdhsa_next_free_vgpr 256
		.amdhsa_next_free_sgpr 102
		.amdhsa_accum_offset 256
		.amdhsa_reserve_vcc 1
		.amdhsa_float_round_mode_32 0
		.amdhsa_float_round_mode_16_64 0
		.amdhsa_float_denorm_mode_32 3
		.amdhsa_float_denorm_mode_16_64 3
		.amdhsa_dx10_clamp 1
		.amdhsa_ieee_mode 1
		.amdhsa_fp16_overflow 0
		.amdhsa_tg_split 0
		.amdhsa_exception_fp_ieee_invalid_op 0
		.amdhsa_exception_fp_denorm_src 0
		.amdhsa_exception_fp_ieee_div_zero 0
		.amdhsa_exception_fp_ieee_overflow 0
		.amdhsa_exception_fp_ieee_underflow 0
		.amdhsa_exception_fp_ieee_inexact 0
		.amdhsa_exception_int_div_zero 0
	.end_amdhsa_kernel

amdhsa.kernels:
  - .agpr_count:     0
    .args:
      - .offset:         0
        .size:           160
        .value_kind:     by_value
      - .offset:         160
        .size:           4
        .value_kind:     hidden_block_count_x
      - .offset:         164
        .size:           4
        .value_kind:     hidden_block_count_y
      - .offset:         168
        .size:           4
        .value_kind:     hidden_block_count_z
      - .offset:         172
        .size:           2
        .value_kind:     hidden_group_size_x
      - .offset:         174
        .size:           2
        .value_kind:     hidden_group_size_y
      - .offset:         176
        .size:           2
        .value_kind:     hidden_group_size_z
      - .offset:         178
        .size:           2
        .value_kind:     hidden_remainder_x
      - .offset:         180
        .size:           2
        .value_kind:     hidden_remainder_y
      - .offset:         182
        .size:           2
        .value_kind:     hidden_remainder_z
      - .offset:         200
        .size:           8
        .value_kind:     hidden_global_offset_x
      - .offset:         208
        .size:           8
        .value_kind:     hidden_global_offset_y
      - .offset:         216
        .size:           8
        .value_kind:     hidden_global_offset_z
      - .offset:         224
        .size:           2
        .value_kind:     hidden_grid_dims
      - .offset:         248
        .size:           8
        .value_kind:     hidden_multigrid_sync_arg
      - .offset:         280
        .size:           4
        .value_kind:     hidden_dynamic_lds_size
    .group_segment_fixed_size: 0
    .kernarg_segment_align: 8
    .kernarg_segment_size: 416
    .language:       OpenCL C
    .language_version:
      - 2
      - 0
    .max_flat_workgroup_size: 512
    .name:           _Z8yoco_fwd6Params
    .private_segment_fixed_size: 0
    .sgpr_count:     108
    .sgpr_spill_count: 373
    .symbol:         _Z8yoco_fwd6Params.kd
    .uniform_work_group_size: 1
    .uses_dynamic_stack: false
    .vgpr_count:     256
    .vgpr_spill_count: 0
    .wavefront_size: 64
